# rmsnorm loads issued together; normaliser scan split over two lightly loaded workgroups
# speedup vs baseline: 1.0086x; 1.0086x over previous
.LBB0_99:
	s_load_dwordx2 s[6:7], s[0:1], 0x148
	v_add_u32_e32 v30, s2, v94
	s_mov_b64 s[24:25], 0x1000
	s_waitcnt lgkmcnt(0)
	v_lshl_add_u64 v[122:123], s[6:7], 0, v[96:97]
	v_cmp_gt_i32_e64 s[6:7], s89, v30
	v_lshl_add_u64 v[124:125], v[122:123], 0, v[98:99]
	v_lshl_add_u64 v[126:127], v[122:123], 0, v[102:103]
	v_lshl_add_u64 v[128:129], v[124:125], 0, s[24:25]
	v_lshl_add_u64 v[130:131], v[126:127], 0, s[24:25]
	global_load_dwordx4 v[82:85], v[124:125], off
	global_load_dwordx4 v[74:77], v[124:125], off offset:1024
	global_load_dwordx4 v[70:73], v[124:125], off offset:2048
	global_load_dwordx4 v[62:65], v[124:125], off offset:3072
	global_load_dwordx4 v[66:69], v[128:129], off
	global_load_dwordx4 v[78:81], v[128:129], off offset:1024
	global_load_dwordx4 v[86:89], v[128:129], off offset:2048
	global_load_dwordx4 v[90:93], v[128:129], off offset:3072
	s_and_saveexec_b64 s[18:19], s[6:7]
	s_cbranch_execz .Lrms0_a
	global_load_dwordx4 v[54:57], v[126:127], off
	global_load_dwordx4 v[42:45], v[126:127], off offset:1024
	global_load_dwordx4 v[34:37], v[126:127], off offset:2048
	global_load_dwordx4 v[30:33], v[126:127], off offset:3072
	global_load_dwordx4 v[38:41], v[130:131], off
	global_load_dwordx4 v[46:49], v[130:131], off offset:1024
	global_load_dwordx4 v[50:53], v[130:131], off offset:2048
	global_load_dwordx4 v[58:61], v[130:131], off offset:3072
.Lrms0_a:
	s_andn2_b64 exec, s[18:19], s[6:7]
	s_waitcnt vmcnt(0)
	s_cbranch_execz .Lrms0_b
	v_mov_b64_e32 v[54:55], v[82:83]
	v_mov_b64_e32 v[56:57], v[84:85]
	v_mov_b64_e32 v[42:43], v[74:75]
	v_mov_b64_e32 v[44:45], v[76:77]
	v_mov_b64_e32 v[34:35], v[70:71]
	v_mov_b64_e32 v[36:37], v[72:73]
	v_mov_b64_e32 v[30:31], v[62:63]
	v_mov_b64_e32 v[32:33], v[64:65]
	v_mov_b64_e32 v[38:39], v[66:67]
	v_mov_b64_e32 v[40:41], v[68:69]
	v_mov_b64_e32 v[46:47], v[78:79]
	v_mov_b64_e32 v[48:49], v[80:81]
	v_mov_b64_e32 v[50:51], v[86:87]
	v_mov_b64_e32 v[52:53], v[88:89]
	v_mov_b64_e32 v[58:59], v[90:91]
	v_mov_b64_e32 v[60:61], v[92:93]
.Lrms0_b:
	s_mov_b64 exec, s[18:19]
	v_mov_b32_e32 v108, v59
	v_mov_b32_e32 v109, v61
	v_mov_b32_e32 v59, v60

.LBB0_817:
	v_readlane_b32 s4, v255, 39
	v_readlane_b32 s5, v255, 40
	s_andn2_b64 vcc, exec, s[4:5]
	s_cbranch_vccnz .LBB0_885
	s_mov_b32 s2, s73
	v_mov_b32_e32 v45, v226
	v_mov_b32_e32 v44, v226
	s_mov_b32 s4, s54
	s_andn2_b32 s4, s2, 16
	s_cmp_lg_u32 s4, 0xe0
	s_cbranch_scc1 .LBB0_857
	s_load_dwordx2 s[4:5], s[0:1], 0x150
	s_load_dwordx2 s[6:7], s[0:1], 0x150
	s_load_dwordx2 s[8:9], s[0:1], 0x150
	s_load_dwordx2 s[10:11], s[0:1], 0x150
	s_load_dwordx2 s[12:13], s[0:1], 0x150
	v_mov_b32_e32 v46, v226
	s_lshl_b32 s19, s2, 5
	s_and_b32 s19, s19, 0x200
	s_nop 0
	v_add_u32_e32 v46, s19, v46
	s_movk_i32 s19, 0x400
	s_nop 0
	v_cmp_gt_i32_e32 vcc, s19, v46
	s_and_saveexec_b64 s[22:23], vcc
	s_cbranch_execz .LBB0_856
	v_mov_b32_e32 v0, 2
	v_cmp_eq_u32_sdwa s[24:25], v46, v169 src0_sel:BYTE_0 src1_sel:DWORD
	v_lshlrev_b32_sdwa v168, v0, v46 dst_sel:DWORD dst_unused:UNUSED_PAD src0_sel:DWORD src1_sel:BYTE_0
	s_mov_b64 s[26:27], 0
	s_branch .LBB0_822
.LBB0_821:
	s_mov_b32 s19, -1
	v_add_u32_e32 v0, 0x200, v46
	v_cmp_lt_i32_e32 vcc, s19, v46
	s_or_b64 s[26:27], vcc, s[26:27]
	v_mov_b32_e32 v46, v0
	s_andn2_b64 exec, exec, s[26:27]
	s_cbranch_execz .LBB0_856
